# attention row-max chain: two redundant v_max (NaN-canonicalising copies) removed per tile
# speedup vs baseline: 1.0063x; 1.0048x over previous
; #define MFMA32(a, b, c) __builtin_amdgcn_mfma_f32_32x32x16_bf16((a), (b), (c), 0, 0, 0)
; __device__ __forceinline__ void attn_unit2(const bf16_t* Qm, const bf16_t* KVm, const bf16_t* P1, bf16_t* OP, int q0, int h, int klat, int nlat, int kctx, int nt, uchar* lds, bool nostore = false) {
;     ...
;         { const uchar* kb = Kt + buf * KT_BYTES + l32 * KROW + hi * 16;
; #pragma unroll
;           for (int s = 0; s < 6; ++s) { const bf16x8 a0 = *(const bf16x8*)(kb + s * 32), a1 = *(const bf16x8*)(kb + 32 * KROW + s * 32);
;               sA0 = MFMA32(a0, qa[s], sA0); sA1 = MFMA32(a1, qa[s], sA1); sB0 = MFMA32(a0, qb[s], sB0); sB1 = MFMA32(a1, qb[s], sB1); } }
.LBB0_1117:
	s_and_b32 s4, s9, 1
	s_mul_i32 s5, s4, 0x3400
	v_add_u32_e32 v0, s5, v226
	ds_read_b128 v[66:69], v0
	ds_read_b128 v[70:73], v0 offset:32
	ds_read_b128 v[74:77], v0 offset:6656
	ds_read_b128 v[234:237], v0 offset:6688
	v_mfma_f32_32x32x16_bf16 v[114:129], v[208:211], v[216:219], 0
	v_mfma_f32_32x32x16_bf16 v[98:113], v[208:211], v[190:193], 0
	s_waitcnt lgkmcnt(3)
	v_mfma_f32_32x32x16_bf16 v[114:129], v[66:69], v[130:133], v[114:129]
	v_mfma_f32_32x32x16_bf16 v[98:113], v[66:69], v[170:173], v[98:113]
	s_waitcnt lgkmcnt(2)
	v_mfma_f32_32x32x16_bf16 v[114:129], v[70:73], v[134:137], v[114:129]
	v_mfma_f32_32x32x16_bf16 v[98:113], v[70:73], v[138:141], v[98:113]
	ds_read_b128 v[66:69], v0 offset:64
	ds_read_b128 v[70:73], v0 offset:96
	ds_read_b128 v[238:241], v0 offset:6720
	ds_read_b128 v[242:245], v0 offset:6752
	s_waitcnt lgkmcnt(3)
	v_mfma_f32_32x32x16_bf16 v[114:129], v[66:69], v[146:149], v[114:129]
	v_mfma_f32_32x32x16_bf16 v[98:113], v[66:69], v[142:145], v[98:113]
	v_mfma_f32_32x32x16_bf16 v[82:97], v[208:211], v[216:219], 0
	v_mfma_f32_32x32x16_bf16 v[82:97], v[74:77], v[130:133], v[82:97]
	s_waitcnt lgkmcnt(2)
	v_mfma_f32_32x32x16_bf16 v[114:129], v[70:73], v[150:153], v[114:129]
	v_mfma_f32_32x32x16_bf16 v[98:113], v[70:73], v[154:157], v[98:113]
	ds_read_b128 v[66:69], v0 offset:128
	ds_read_b128 v[70:73], v0 offset:160
	ds_read_b128 v[246:249], v0 offset:6784
	ds_read_b128 v[212:215], v0 offset:6816
	v_mfma_f32_32x32x16_bf16 v[82:97], v[234:237], v[134:137], v[82:97]
	s_waitcnt lgkmcnt(3)
	v_mfma_f32_32x32x16_bf16 v[114:129], v[66:69], v[162:165], v[114:129]
	v_mfma_f32_32x32x16_bf16 v[98:113], v[66:69], v[158:161], v[98:113]
	v_mfma_f32_32x32x16_bf16 v[82:97], v[238:241], v[146:149], v[82:97]
	s_waitcnt lgkmcnt(2)
	v_mfma_f32_32x32x16_bf16 v[114:129], v[70:73], v[166:169], v[114:129]
	v_mfma_f32_32x32x16_bf16 v[98:113], v[70:73], v[174:177], v[98:113]
	s_nop 10
	v_max_f32_e32 v0, v114, v115
	v_mfma_f32_32x32x16_bf16 v[66:81], v[74:77], v[170:173], 0
	v_mfma_f32_32x32x16_bf16 v[66:81], v[208:211], v[190:193], v[66:81]
	v_mfma_f32_32x32x16_bf16 v[82:97], v[242:245], v[150:153], v[82:97]
	v_mfma_f32_32x32x16_bf16 v[66:81], v[234:237], v[138:141], v[66:81]
	s_waitcnt lgkmcnt(1)
	v_mfma_f32_32x32x16_bf16 v[82:97], v[246:249], v[162:165], v[82:97]
	v_mfma_f32_32x32x16_bf16 v[66:81], v[238:241], v[142:145], v[66:81]
	s_waitcnt lgkmcnt(0)
	v_mfma_f32_32x32x16_bf16 v[82:97], v[212:215], v[166:169], v[82:97]
	v_mfma_f32_32x32x16_bf16 v[66:81], v[242:245], v[154:157], v[66:81]
	s_nop 10
	v_max3_f32 v234, v116, v117, v83
	v_max3_f32 v0, v0, v82, v84
	v_max3_f32 v0, v0, v85, v118
	v_max3_f32 v234, v234, v120, v121
	v_max3_f32 v0, v0, v119, v86
	v_max3_f32 v234, v234, v88, v89
	v_max3_f32 v0, v0, v87, v122
	v_mfma_f32_32x32x16_bf16 v[66:81], v[246:249], v[158:161], v[66:81]
	v_mfma_f32_32x32x16_bf16 v[66:81], v[212:215], v[174:177], v[66:81]
	v_max3_f32 v234, v234, v124, v125
	v_max3_f32 v0, v0, v123, v90
	v_max3_f32 v234, v234, v92, v93
	v_max3_f32 v0, v0, v91, v126
	v_max3_f32 v234, v234, v128, v129
	v_max3_f32 v0, v0, v127, v94
	v_max3_f32 v234, v234, v96, v97
	v_max3_f32 v0, v0, v95, v234
	v_max3_f32 v235, v98, v99, v100
	v_max3_f32 v236, v101, v102, v103
	v_max3_f32 v235, v235, v104, v105
	v_max3_f32 v236, v236, v106, v107
	v_max3_f32 v235, v235, v108, v109
	v_max3_f32 v236, v236, v110, v111
	v_max3_f32 v235, v235, v112, v113
	v_max3_f32 v236, v236, v66, v67
	v_max3_f32 v235, v235, v68, v69
	v_max3_f32 v236, v236, v70, v71
	v_max3_f32 v235, v235, v72, v73
	v_max3_f32 v236, v236, v74, v75
	v_max3_f32 v235, v235, v76, v77
	v_max3_f32 v236, v236, v78, v79
	v_max3_f32 v235, v235, v80, v81
	v_max_f32_e32 v235, v235, v236
	v_max_f32_e32 v236, v0, v235
	v_cmp_lt_f32_e32 vcc, 0x41000000, v236
	s_cmp_eq_u32 s9, 0
	s_cbranch_scc1 .Latt_rare
	s_cbranch_vccz .LBB0_1121
